# rotated tile loops: the four LDS read-backs of a tile issued together behind one wait
# baseline (speedup 1.0000x reference)
; __device__ __forceinline__ unsigned cvt_pk_bf16(float lo, float hi) { unsigned r; asm volatile("v_cvt_pk_bf16_f32 %0, %1, %2" : "=v"(r) : "v"(lo), "v"(hi)); return r; }
; __device__ __forceinline__ void transpose_tile(const float* src, int ldsrc, int k0, int n0, bf16_t* dst, int ldd, const float* gain, int rowmode, float* T) {
;     ...
;     { const int n = tid >> 3, k8 = (tid & 7) * 8; const float* tp = T + n * 65 + k8; u32x4 w;
;         w.x = cvt_pk_bf16(tp[0], tp[1]); w.y = cvt_pk_bf16(tp[2], tp[3]); w.z = cvt_pk_bf16(tp[4], tp[5]); w.w = cvt_pk_bf16(tp[6], tp[7]);
;         const int nn = n0 + n; int row;
;         if (rowmode == 1) row = (nn >> 7) * 256 + (nn & 127);
;         else if (rowmode == 2) row = (nn >> 7) * 256 + 128 + (nn & 127);
;         else if (rowmode == 3) row = nn < 1024 ? nn : (nn < 2048 ? nn + 1024 : nn - 1024);
;         else row = nn;
.Lrot0_tail:
	s_mov_b64 s[98:99], -1
	ds_read2_b32 v[136:137], v10 offset1:1
	ds_read2_b32 v[138:139], v10 offset0:2 offset1:3
	ds_read2_b32 v[156:157], v10 offset0:4 offset1:5
	ds_read2_b32 v[150:151], v10 offset0:6 offset1:7
	s_waitcnt lgkmcnt(0)
	v_cvt_pk_bf16_f32 v136, v136, v137
	v_cvt_pk_bf16_f32 v137, v138, v139
	v_cvt_pk_bf16_f32 v138, v156, v157
	v_cvt_pk_bf16_f32 v139, v150, v151
	v_add_u32_e32 v150, v200, v9
	s_cmp_lt_i32 s97, 2
	s_cbranch_scc1 .LBB0_1226
	s_cmp_gt_i32 s97, 2
	s_cbranch_scc0 .LBB0_1223
	v_cmp_gt_u32_e32 vcc, s64, v150
	s_mov_b64 s[98:99], 0
	s_nop 0
	v_cndmask_b32_e32 v151, v12, v13, vcc
	v_cmp_lt_u32_e32 vcc, s65, v150
	s_nop 1
	v_cndmask_b32_e32 v151, 0, v151, vcc
	v_add_u32_e32 v151, v151, v150

; __device__ __forceinline__ unsigned cvt_pk_bf16(float lo, float hi) { unsigned r; asm volatile("v_cvt_pk_bf16_f32 %0, %1, %2" : "=v"(r) : "v"(lo), "v"(hi)); return r; }
; __device__ __forceinline__ void transpose_tile(const float* src, int ldsrc, int k0, int n0, bf16_t* dst, int ldd, const float* gain, int rowmode, float* T) {
;     ...
;     { const int n = tid >> 3, k8 = (tid & 7) * 8; const float* tp = T + n * 65 + k8; u32x4 w;
;         w.x = cvt_pk_bf16(tp[0], tp[1]); w.y = cvt_pk_bf16(tp[2], tp[3]); w.z = cvt_pk_bf16(tp[4], tp[5]); w.w = cvt_pk_bf16(tp[6], tp[7]);
;         const int nn = n0 + n; int row;
;         if (rowmode == 1) row = (nn >> 7) * 256 + (nn & 127);
;         else if (rowmode == 2) row = (nn >> 7) * 256 + 128 + (nn & 127);
;         else if (rowmode == 3) row = nn < 1024 ? nn : (nn < 2048 ? nn + 1024 : nn - 1024);
;         else row = nn;
.Lrot6_tail:
	s_mov_b64 s[98:99], -1
	ds_read2_b32 v[136:137], v10 offset1:1
	ds_read2_b32 v[138:139], v10 offset0:2 offset1:3
	ds_read2_b32 v[156:157], v10 offset0:4 offset1:5
	ds_read2_b32 v[150:151], v10 offset0:6 offset1:7
	s_waitcnt lgkmcnt(0)
	v_cvt_pk_bf16_f32 v136, v136, v137
	v_cvt_pk_bf16_f32 v137, v138, v139
	v_cvt_pk_bf16_f32 v138, v156, v157
	v_cvt_pk_bf16_f32 v139, v150, v151
	v_add_u32_e32 v150, v200, v9
	s_cmp_lt_i32 s97, 2
	s_cbranch_scc1 .LBB0_2014
	s_cmp_gt_i32 s97, 2
	s_cbranch_scc0 .LBB0_2011
	v_cmp_gt_u32_e32 vcc, s65, v150
	s_mov_b64 s[98:99], 0
	s_nop 0
	v_cndmask_b32_e32 v151, v12, v13, vcc
	v_cmp_lt_u32_e32 vcc, s76, v150
	s_nop 1
	v_cndmask_b32_e32 v151, 0, v151, vcc
	v_add_u32_e32 v151, v151, v150

; __device__ __forceinline__ unsigned cvt_pk_bf16(float lo, float hi) { unsigned r; asm volatile("v_cvt_pk_bf16_f32 %0, %1, %2" : "=v"(r) : "v"(lo), "v"(hi)); return r; }
; __device__ __forceinline__ void transpose_tile(const float* src, int ldsrc, int k0, int n0, bf16_t* dst, int ldd, const float* gain, int rowmode, float* T) {
;     ...
;     { const int n = tid >> 3, k8 = (tid & 7) * 8; const float* tp = T + n * 65 + k8; u32x4 w;
;         w.x = cvt_pk_bf16(tp[0], tp[1]); w.y = cvt_pk_bf16(tp[2], tp[3]); w.z = cvt_pk_bf16(tp[4], tp[5]); w.w = cvt_pk_bf16(tp[6], tp[7]);
;         const int nn = n0 + n; int row;
;         if (rowmode == 1) row = (nn >> 7) * 256 + (nn & 127);
;         else if (rowmode == 2) row = (nn >> 7) * 256 + 128 + (nn & 127);
;         else if (rowmode == 3) row = nn < 1024 ? nn : (nn < 2048 ? nn + 1024 : nn - 1024);
;         else row = nn;
.Lrot8_tail:
	s_mov_b64 s[98:99], -1
	ds_read2_b32 v[136:137], v9 offset1:1
	ds_read2_b32 v[138:139], v9 offset0:2 offset1:3
	ds_read2_b32 v[156:157], v9 offset0:4 offset1:5
	ds_read2_b32 v[150:151], v9 offset0:6 offset1:7
	v_add_u32_e32 v149, v200, v8
	s_waitcnt lgkmcnt(0)
	v_cvt_pk_bf16_f32 v136, v136, v137
	v_cvt_pk_bf16_f32 v137, v138, v139
	v_cvt_pk_bf16_f32 v138, v156, v157
	v_cvt_pk_bf16_f32 v139, v150, v151
	s_cmp_lt_i32 s97, 2
	s_cbranch_scc1 .LBB0_2217
	s_cmp_gt_i32 s97, 2
	s_cbranch_scc0 .LBB0_2214
	v_cmp_gt_u32_e32 vcc, s76, v149
	s_mov_b64 s[98:99], 0
	s_nop 0
	v_cndmask_b32_e32 v150, v11, v12, vcc
	v_cmp_lt_u32_e32 vcc, s77, v149
	s_nop 1
	v_cndmask_b32_e32 v150, 0, v150, vcc
	v_add_u32_e32 v150, v150, v149
